# importance pass cross-lane sums via DPP row_ror and v_permlane16_swap instead of ds_bpermute
# baseline (speedup 1.0000x reference)
; #define LAS __attribute__((address_space(3)))
; __device__ __forceinline__ float shflx(float v, int mask, int lane) { return __builtin_bit_cast(float, __builtin_amdgcn_ds_bpermute(((lane ^ mask) & 63) << 2, __builtin_bit_cast(int, v))); }
; template <int MODE  > ...
;     ...
;             for (int kk = 0; kk < 4; ++kk) {
;                 const bf16x8 k0 = *(const LAS bf16x8*)(kb + col * KPITCH + kk * 16 + h * 8);
;                 const bf16x8 k1 = *(const LAS bf16x8*)(kb + (32 + col) * KPITCH + kk * 16 + h * 8);
;                 s0 = __builtin_amdgcn_mfma_f32_32x32x16_bf16(k0, qf[kk], s0, 0, 0, 0);
;                 s1 = __builtin_amdgcn_mfma_f32_32x32x16_bf16(k1, qf[kk], s1, 0, 0, 0);
;             }
;     ...
;                 const float inv = st.l > 0.f ? 1.f / st.l : 0.f;
;                 LAS float* impA = (LAS float*)(lds + A_IMPA); LAS float* impB = (LAS float*)(lds + A_IMPB);
;                 const int q = 8 * w + (col & 7);
; #pragma unroll
;                 for (int kt = 0; kt < 2; ++kt)
; #pragma unroll
;                     for (int gi = 0; gi < 4; ++gi) {
;                         float p[4];
; #pragma unroll
;                         for (int e = 0; e < 4; ++e) { const int i = 4 * gi + e; const float sv = kt ? s1[i] : s0[i]; p[e] = __builtin_amdgcn_exp2f(sv) * inv; }
;                         float av = (p[0] + p[1]) + (p[2] + 0.5f * p[3]), bv = 0.5f * p[3];
;                         av += shflx(av, 8, lane); av += shflx(av, 16, lane);
;                         bv += shflx(bv, 8, lane); bv += shflx(bv, 16, lane);
;                         const int jj = 16 * j + 8 * kt + 2 * gi + h;
;                         if (col < 8 && jj < 64) { impA[q * IMPP + jj] = av; if (jj + 1 < 64) impB[q * IMPP + jj + 1] = bv; }
;                     }
.LBB0_171:
	s_mul_i32 s4, s22, 0x2400
	v_add_u32_e32 v54, s4, v66
	ds_read_b128 v[42:45], v54 offset:4608
	ds_read_b128 v[46:49], v54
	ds_read_b128 v[50:53], v54 offset:32
	s_waitcnt lgkmcnt(0)
	v_mfma_f32_32x32x16_bf16 v[2:17], v[42:45], v[144:147], v[2:17]
	ds_read_b128 v[42:45], v54 offset:4640
	v_mfma_f32_32x32x16_bf16 v[18:33], v[46:49], v[144:147], v[18:33]
	v_mfma_f32_32x32x16_bf16 v[18:33], v[50:53], v[148:151], v[18:33]
	s_waitcnt lgkmcnt(0)
	v_mfma_f32_32x32x16_bf16 v[2:17], v[42:45], v[148:151], v[2:17]
	ds_read_b128 v[42:45], v54 offset:64
	ds_read_b128 v[46:49], v54 offset:4672
	s_waitcnt lgkmcnt(0)
	v_mfma_f32_32x32x16_bf16 v[18:33], v[42:45], v[152:155], v[18:33]
	v_mfma_f32_32x32x16_bf16 v[2:17], v[46:49], v[152:155], v[2:17]
	ds_read_b128 v[42:45], v54 offset:96
	ds_read_b128 v[46:49], v54 offset:4704
	s_waitcnt lgkmcnt(0)
	v_mfma_f32_32x32x16_bf16 v[18:33], v[42:45], v[156:159], v[18:33]
	v_lshl_add_u32 v42, s84, 4, v41
	v_cmp_gt_i32_e32 vcc, 64, v42
	s_and_b64 s[84:85], s[14:15], vcc
	v_mfma_f32_32x32x16_bf16 v[2:17], v[46:49], v[156:159], v[2:17]
	s_nop 7
	v_exp_f32_e32 v19, v19
	v_exp_f32_e32 v21, v21
	v_exp_f32_e32 v18, v18
	v_exp_f32_e32 v20, v20
	v_mul_f32_e32 v19, v64, v19
	v_mul_f32_e32 v43, v64, v21
	v_fmac_f32_e32 v19, v64, v18
	v_mul_f32_e32 v18, 0.5, v43
	v_fma_f32 v20, v64, v20, v18
	v_add_f32_e32 v19, v19, v20
	s_nop 1
	v_mov_b32_dpp v20, v19 row_ror:8 row_mask:0xf bank_mask:0xf
	s_nop 1
	v_mov_b32_dpp v21, v18 row_ror:8 row_mask:0xf bank_mask:0xf
	v_add_u32_e32 v18, v42, v62
	v_lshl_add_u32 v18, v18, 2, 0
	s_waitcnt lgkmcnt(0)
	v_add_f32_e32 v19, v19, v20
	v_fmac_f32_e32 v21, 0.5, v43
	v_mov_b32_e32 v20, v19
	s_nop 1
	v_permlane16_swap_b32_e32 v20, v19
	v_mov_b32_e32 v43, v21
	s_nop 1
	v_permlane16_swap_b32_e32 v43, v21
	s_and_saveexec_b64 s[4:5], s[84:85]
	s_cbranch_execz .LBB0_174
	s_waitcnt lgkmcnt(0)
	v_add_f32_e32 v19, v19, v20
	v_cmp_ne_u32_e32 vcc, 63, v42
	ds_write_b32 v18, v19 offset:43008
	s_and_b64 exec, exec, vcc
	v_add_f32_e32 v19, v21, v43
	ds_write_b32 v18, v19 offset:59652
.LBB0_174:
	s_or_b64 exec, exec, s[4:5]
	v_exp_f32_e32 v19, v23
	s_waitcnt lgkmcnt(0)
	v_exp_f32_e32 v20, v25
	v_exp_f32_e32 v21, v22
	v_exp_f32_e32 v22, v24
	v_mul_f32_e32 v19, v64, v19
	v_mul_f32_e32 v20, v64, v20
	v_fmac_f32_e32 v19, v64, v21
	v_mul_f32_e32 v21, 0.5, v20
	v_fma_f32 v22, v64, v22, v21
	v_add_f32_e32 v22, v19, v22
	s_nop 1
	v_mov_b32_dpp v19, v21 row_ror:8 row_mask:0xf bank_mask:0xf
	s_nop 1
	v_mov_b32_dpp v21, v22 row_ror:8 row_mask:0xf bank_mask:0xf
	v_cmp_gt_i32_e32 vcc, 62, v42
	s_and_b64 s[84:85], s[14:15], vcc
	s_waitcnt lgkmcnt(0)
	v_fmac_f32_e32 v19, 0.5, v20
	v_add_f32_e32 v21, v22, v21
	v_mov_b32_e32 v22, v21
	s_nop 1
	v_permlane16_swap_b32_e32 v22, v21
	v_mov_b32_e32 v20, v19
	s_nop 1
	v_permlane16_swap_b32_e32 v20, v19
	s_and_saveexec_b64 s[4:5], s[84:85]
	s_cbranch_execz .LBB0_177
	s_waitcnt lgkmcnt(0)
	v_add_f32_e32 v21, v21, v22
	v_cmp_ne_u32_e32 vcc, 61, v42
	ds_write_b32 v18, v21 offset:43016
	s_and_b64 exec, exec, vcc
	v_add_f32_e32 v19, v19, v20
	ds_write_b32 v18, v19 offset:59660
.LBB0_177:
	s_or_b64 exec, exec, s[4:5]
	v_exp_f32_e32 v19, v27
	s_waitcnt lgkmcnt(0)
	v_exp_f32_e32 v20, v29
	v_exp_f32_e32 v21, v26
	v_exp_f32_e32 v22, v28
	v_mul_f32_e32 v19, v64, v19
	v_mul_f32_e32 v20, v64, v20
	v_fmac_f32_e32 v19, v64, v21
	v_mul_f32_e32 v21, 0.5, v20
	v_fma_f32 v22, v64, v22, v21
	v_add_f32_e32 v22, v19, v22
	s_nop 1
	v_mov_b32_dpp v19, v21 row_ror:8 row_mask:0xf bank_mask:0xf
	s_nop 1
	v_mov_b32_dpp v21, v22 row_ror:8 row_mask:0xf bank_mask:0xf
	v_cmp_gt_i32_e32 vcc, 60, v42
	s_and_b64 s[84:85], s[14:15], vcc
	s_waitcnt lgkmcnt(0)
	v_fmac_f32_e32 v19, 0.5, v20
	v_add_f32_e32 v21, v22, v21
	v_mov_b32_e32 v22, v21
	s_nop 1
	v_permlane16_swap_b32_e32 v22, v21
	v_mov_b32_e32 v20, v19
	s_nop 1
	v_permlane16_swap_b32_e32 v20, v19
	s_and_saveexec_b64 s[4:5], s[84:85]
	s_cbranch_execz .LBB0_180
	s_waitcnt lgkmcnt(0)
	v_add_f32_e32 v21, v21, v22
	v_cmp_ne_u32_e32 vcc, 59, v42
	ds_write_b32 v18, v21 offset:43024
	s_and_b64 exec, exec, vcc
	v_add_f32_e32 v19, v19, v20
	ds_write_b32 v18, v19 offset:59668
; __device__ __forceinline__ float shflx(float v, int mask, int lane) { return __builtin_bit_cast(float, __builtin_amdgcn_ds_bpermute(((lane ^ mask) & 63) << 2, __builtin_bit_cast(int, v))); }
; template <int MODE  > ...
;     ...
; #pragma unroll
;                 for (int kt = 0; kt < 2; ++kt)
; #pragma unroll
;                     for (int gi = 0; gi < 4; ++gi) {
;                         float p[4];
; #pragma unroll
;                         for (int e = 0; e < 4; ++e) { const int i = 4 * gi + e; const float sv = kt ? s1[i] : s0[i]; p[e] = __builtin_amdgcn_exp2f(sv) * inv; }
;                         float av = (p[0] + p[1]) + (p[2] + 0.5f * p[3]), bv = 0.5f * p[3];
;                         av += shflx(av, 8, lane); av += shflx(av, 16, lane);
;                         bv += shflx(bv, 8, lane); bv += shflx(bv, 16, lane);
;                         const int jj = 16 * j + 8 * kt + 2 * gi + h;
;                         if (col < 8 && jj < 64) { impA[q * IMPP + jj] = av; if (jj + 1 < 64) impB[q * IMPP + jj + 1] = bv; }
;                     }
.LBB0_180:
	s_or_b64 exec, exec, s[4:5]
	v_exp_f32_e32 v19, v31
	s_waitcnt lgkmcnt(0)
	v_exp_f32_e32 v20, v33
	v_exp_f32_e32 v21, v30
	v_exp_f32_e32 v22, v32
	v_mul_f32_e32 v19, v64, v19
	v_mul_f32_e32 v20, v64, v20
	v_fmac_f32_e32 v19, v64, v21
	v_mul_f32_e32 v21, 0.5, v20
	v_fma_f32 v22, v64, v22, v21
	v_add_f32_e32 v22, v19, v22
	s_nop 1
	v_mov_b32_dpp v19, v21 row_ror:8 row_mask:0xf bank_mask:0xf
	s_nop 1
	v_mov_b32_dpp v21, v22 row_ror:8 row_mask:0xf bank_mask:0xf
	v_cmp_gt_i32_e32 vcc, 58, v42
	s_and_b64 s[84:85], s[14:15], vcc
	s_waitcnt lgkmcnt(0)
	v_fmac_f32_e32 v19, 0.5, v20
	v_add_f32_e32 v21, v22, v21
	v_mov_b32_e32 v22, v21
	s_nop 1
	v_permlane16_swap_b32_e32 v22, v21
	v_mov_b32_e32 v20, v19
	s_nop 1
	v_permlane16_swap_b32_e32 v20, v19
	s_and_saveexec_b64 s[4:5], s[84:85]
	s_cbranch_execz .LBB0_183
	s_waitcnt lgkmcnt(0)
	v_add_f32_e32 v21, v21, v22
	v_cmp_ne_u32_e32 vcc, 57, v42
	ds_write_b32 v18, v21 offset:43032
	s_and_b64 exec, exec, vcc
	v_add_f32_e32 v19, v19, v20
	ds_write_b32 v18, v19 offset:59676
.LBB0_183:
	s_or_b64 exec, exec, s[4:5]
	v_exp_f32_e32 v3, v3
	v_exp_f32_e32 v5, v5
	v_exp_f32_e32 v2, v2
	v_exp_f32_e32 v4, v4
	v_mul_f32_e32 v3, v64, v3
	v_mul_f32_e32 v5, v64, v5
	v_fmac_f32_e32 v3, v64, v2
	v_mul_f32_e32 v2, 0.5, v5
	v_fma_f32 v4, v64, v4, v2
	v_add_f32_e32 v3, v3, v4
	s_nop 1
	v_mov_b32_dpp v2, v2 row_ror:8 row_mask:0xf bank_mask:0xf
	s_nop 1
	v_mov_b32_dpp v4, v3 row_ror:8 row_mask:0xf bank_mask:0xf
	v_cmp_gt_i32_e32 vcc, 56, v42
	s_and_b64 s[84:85], s[14:15], vcc
	s_waitcnt lgkmcnt(0)
	v_fmac_f32_e32 v2, 0.5, v5
	v_add_f32_e32 v4, v3, v4
	v_mov_b32_e32 v5, v4
	s_nop 1
	v_permlane16_swap_b32_e32 v5, v4
	v_mov_b32_e32 v3, v2
	s_nop 1
	v_permlane16_swap_b32_e32 v3, v2
	s_and_saveexec_b64 s[4:5], s[84:85]
	s_cbranch_execz .LBB0_186
	s_waitcnt lgkmcnt(0)
	v_add_f32_e32 v4, v4, v5
	v_cmp_ne_u32_e32 vcc, 55, v42
	ds_write_b32 v18, v4 offset:43040
	s_and_b64 exec, exec, vcc
	v_add_f32_e32 v2, v2, v3
	ds_write_b32 v18, v2 offset:59684
.LBB0_186:
	s_or_b64 exec, exec, s[4:5]
	v_exp_f32_e32 v2, v7
	s_waitcnt lgkmcnt(0)
	v_exp_f32_e32 v3, v9
	v_exp_f32_e32 v4, v6
	v_exp_f32_e32 v5, v8
	v_mul_f32_e32 v2, v64, v2
	v_mul_f32_e32 v3, v64, v3
	v_fmac_f32_e32 v2, v64, v4
	v_mul_f32_e32 v4, 0.5, v3
	v_fma_f32 v5, v64, v5, v4
	v_add_f32_e32 v5, v2, v5
	s_nop 1
	v_mov_b32_dpp v2, v4 row_ror:8 row_mask:0xf bank_mask:0xf
	s_nop 1
	v_mov_b32_dpp v4, v5 row_ror:8 row_mask:0xf bank_mask:0xf
	v_cmp_gt_i32_e32 vcc, 54, v42
	s_and_b64 s[84:85], s[14:15], vcc
	s_waitcnt lgkmcnt(0)
	v_fmac_f32_e32 v2, 0.5, v3
	v_add_f32_e32 v4, v5, v4
	v_mov_b32_e32 v5, v4
	s_nop 1
	v_permlane16_swap_b32_e32 v5, v4
	v_mov_b32_e32 v3, v2
	s_nop 1
	v_permlane16_swap_b32_e32 v3, v2
	s_and_saveexec_b64 s[4:5], s[84:85]
	s_cbranch_execz .LBB0_189
	s_waitcnt lgkmcnt(0)
	v_add_f32_e32 v4, v4, v5
	v_cmp_ne_u32_e32 vcc, 53, v42
	ds_write_b32 v18, v4 offset:43048
	s_and_b64 exec, exec, vcc
	v_add_f32_e32 v2, v2, v3
	ds_write_b32 v18, v2 offset:59692
.LBB0_189:
	s_or_b64 exec, exec, s[4:5]
	v_exp_f32_e32 v2, v11
	s_waitcnt lgkmcnt(0)
	v_exp_f32_e32 v3, v13
	v_exp_f32_e32 v4, v10
	v_exp_f32_e32 v5, v12
	v_mul_f32_e32 v2, v64, v2
	v_mul_f32_e32 v3, v64, v3
	v_fmac_f32_e32 v2, v64, v4
	v_mul_f32_e32 v4, 0.5, v3
	v_fma_f32 v5, v64, v5, v4
	v_add_f32_e32 v5, v2, v5
	s_nop 1
	v_mov_b32_dpp v2, v4 row_ror:8 row_mask:0xf bank_mask:0xf
	s_nop 1
	v_mov_b32_dpp v4, v5 row_ror:8 row_mask:0xf bank_mask:0xf
	v_cmp_gt_i32_e32 vcc, 52, v42
	s_and_b64 s[84:85], s[14:15], vcc
	s_waitcnt lgkmcnt(0)
	v_fmac_f32_e32 v2, 0.5, v3
	v_add_f32_e32 v4, v5, v4
	v_mov_b32_e32 v5, v4
	s_nop 1
	v_permlane16_swap_b32_e32 v5, v4
	v_mov_b32_e32 v3, v2
	s_nop 1
	v_permlane16_swap_b32_e32 v3, v2
	s_and_saveexec_b64 s[4:5], s[84:85]
	s_cbranch_execz .LBB0_192
	s_waitcnt lgkmcnt(0)
	v_add_f32_e32 v4, v4, v5
	v_cmp_ne_u32_e32 vcc, 51, v42
	ds_write_b32 v18, v4 offset:43056
	s_and_b64 exec, exec, vcc
	v_add_f32_e32 v2, v2, v3
	ds_write_b32 v18, v2 offset:59700
.LBB0_192:
	s_or_b64 exec, exec, s[4:5]
	v_exp_f32_e32 v2, v15
	s_waitcnt lgkmcnt(0)
	v_exp_f32_e32 v3, v17
	v_exp_f32_e32 v4, v14
	v_exp_f32_e32 v5, v16
	v_mul_f32_e32 v2, v64, v2
	v_mul_f32_e32 v3, v64, v3
	v_fmac_f32_e32 v2, v64, v4
	v_mul_f32_e32 v4, 0.5, v3
	v_fma_f32 v5, v64, v5, v4
	v_add_f32_e32 v5, v2, v5
	s_nop 1
	v_mov_b32_dpp v2, v4 row_ror:8 row_mask:0xf bank_mask:0xf
	s_nop 1
	v_mov_b32_dpp v4, v5 row_ror:8 row_mask:0xf bank_mask:0xf
	v_cmp_gt_i32_e32 vcc, 50, v42
	s_and_b64 s[84:85], s[14:15], vcc
	s_waitcnt lgkmcnt(0)
	v_fmac_f32_e32 v2, 0.5, v3
	v_add_f32_e32 v4, v5, v4
	v_mov_b32_e32 v5, v4
	s_nop 1
	v_permlane16_swap_b32_e32 v5, v4
	v_mov_b32_e32 v3, v2
	s_nop 1
	v_permlane16_swap_b32_e32 v3, v2
	s_and_saveexec_b64 s[4:5], s[84:85]
	s_cbranch_execz .LBB0_195
	s_waitcnt lgkmcnt(0)
	v_add_f32_e32 v4, v4, v5
	v_cmp_ne_u32_e32 vcc, 49, v42
	ds_write_b32 v18, v4 offset:43064
	s_and_b64 exec, exec, vcc
	v_add_f32_e32 v2, v2, v3
	ds_write_b32 v18, v2 offset:59708
